# forget-logit MFMA pass moved to the tail of step 17 (before its grid barrier): no repeated step, no extra barrier
# speedup vs baseline: 1.0165x; 1.0082x over previous
; template <int MODE> __device__ __forceinline__ void gemm_epilogue(f32x4 (&acc)[2][2][4][2], const GD& g, const pg8::Unit& u, int wr, int wc, int fr, int fq, LAS unsigned char* lds, const float (&rsv)[2][4]) {
;     ...
;         } else if (wc == 0 && fq < 2) {
;             float* FL = (float*)g.o3; const float* bfv = g.f0;
; #pragma unroll
;             for (int ai = 0; ai < 2; ++ai)
; #pragma unroll
;                 for (int m = 0; m < 4; ++m) { const int row = rt + ai * 128 + m * 16;
; #pragma unroll
;                     for (int n = 0; n < 2; ++n) { f32x4 v = acc[ai][0][m][n];
.LBB0_1306:
	s_cmp_eq_u32 s46, 17
	s_cbranch_scc0 .Lfl_done
	s_load_dwordx2 s[30:31], s[44:45], 0xc0
	v_and_b32_e32 v155, 63, v194
	v_readfirstlane_b32 s2, v194
	s_lshr_b32 s2, s2, 6
	s_cmp_gt_u32 s2, 3
	s_cbranch_scc1 .Lfl_done
	v_readlane_b32 s3, v253, 4
	v_and_b32_e32 v130, 15, v155
	v_lshrrev_b32_e32 v131, 4, v155
	s_lshr_b32 s3, s3, 3
	s_lshl_b32 s6, s3, 6
	s_lshl_b32 s7, s2, 4
	s_add_i32 s6, s6, s7
	s_lshl_b32 s7, s2, 6
	v_lshlrev_b32_e32 v146, 14, v130
	v_lshl_add_u32 v146, v131, 4, v146
	v_add_u32_e32 v146, s7, v146
	s_lshr_b32 s0, s3, 6
	s_lshl_b32 s0, s0, 18
	s_and_b32 s1, s3, 63
	s_lshl_b32 s1, s1, 8
	s_add_i32 s7, s0, s1
	s_add_i32 s7, s7, 0x100000
	v_add_u32_e32 v132, s6, v130
	v_lshlrev_b32_e32 v132, 12, v132
	v_lshl_add_u32 v132, v131, 4, v132
	v_lshlrev_b32_e32 v133, 7, v130
	v_lshl_add_u32 v133, v131, 4, v133
	s_waitcnt lgkmcnt(0)
	s_add_u32 s8, s30, 0x11e00000
	s_addc_u32 s9, s31, 0
	s_add_u32 s10, s30, 0x3900000
	s_addc_u32 s11, s31, 0
	v_mov_b32_e32 v134, 0
	v_mov_b32_e32 v135, 0
	v_mov_b32_e32 v136, 0
	v_mov_b32_e32 v137, 0
	global_load_dwordx4 v[2:5], v132, s[8:9]
	global_load_dwordx4 v[6:9], v132, s[8:9] offset:64
	global_load_dwordx4 v[10:13], v132, s[8:9] offset:128
	global_load_dwordx4 v[14:17], v132, s[8:9] offset:192
	global_load_dwordx4 v[18:21], v132, s[8:9] offset:256
	global_load_dwordx4 v[22:25], v132, s[8:9] offset:320
	global_load_dwordx4 v[26:29], v132, s[8:9] offset:384
	global_load_dwordx4 v[30:33], v132, s[8:9] offset:448
	global_load_dwordx4 v[34:37], v132, s[8:9] offset:512
	global_load_dwordx4 v[38:41], v132, s[8:9] offset:576
	global_load_dwordx4 v[42:45], v132, s[8:9] offset:640
	global_load_dwordx4 v[46:49], v132, s[8:9] offset:704
	global_load_dwordx4 v[50:53], v132, s[8:9] offset:768
	global_load_dwordx4 v[54:57], v132, s[8:9] offset:832
	global_load_dwordx4 v[58:61], v132, s[8:9] offset:896
	global_load_dwordx4 v[62:65], v132, s[8:9] offset:960
	global_load_dwordx4 v[66:69], v133, s[10:11]
	global_load_dwordx4 v[70:73], v133, s[10:11] offset:64
	v_add_u32_e32 v133, 0x8000, v133
	global_load_dwordx4 v[74:77], v133, s[10:11]
	global_load_dwordx4 v[78:81], v133, s[10:11] offset:64
	v_add_u32_e32 v133, 0x8000, v133
	global_load_dwordx4 v[82:85], v133, s[10:11]
	global_load_dwordx4 v[86:89], v133, s[10:11] offset:64
	v_add_u32_e32 v133, 0x8000, v133
	global_load_dwordx4 v[90:93], v133, s[10:11]
	global_load_dwordx4 v[94:97], v133, s[10:11] offset:64
	v_add_u32_e32 v133, 0x8000, v133
	global_load_dwordx4 v[98:101], v133, s[10:11]
	global_load_dwordx4 v[102:105], v133, s[10:11] offset:64
	v_add_u32_e32 v133, 0x8000, v133
	global_load_dwordx4 v[106:109], v133, s[10:11]
	global_load_dwordx4 v[110:113], v133, s[10:11] offset:64
	v_add_u32_e32 v133, 0x8000, v133
	global_load_dwordx4 v[114:117], v133, s[10:11]
	global_load_dwordx4 v[118:121], v133, s[10:11] offset:64
	v_add_u32_e32 v133, 0x8000, v133
	global_load_dwordx4 v[122:125], v133, s[10:11]
	global_load_dwordx4 v[126:129], v133, s[10:11] offset:64
	v_add_u32_e32 v133, 0x8000, v133
	s_waitcnt vmcnt(0)
	v_mfma_f32_16x16x32_bf16 v[134:137], v[2:5], v[66:69], v[134:137]
	v_mfma_f32_16x16x32_bf16 v[134:137], v[6:9], v[70:73], v[134:137]
	v_mfma_f32_16x16x32_bf16 v[134:137], v[10:13], v[74:77], v[134:137]
	v_mfma_f32_16x16x32_bf16 v[134:137], v[14:17], v[78:81], v[134:137]
	v_mfma_f32_16x16x32_bf16 v[134:137], v[18:21], v[82:85], v[134:137]
	v_mfma_f32_16x16x32_bf16 v[134:137], v[22:25], v[86:89], v[134:137]
	v_mfma_f32_16x16x32_bf16 v[134:137], v[26:29], v[90:93], v[134:137]
	v_mfma_f32_16x16x32_bf16 v[134:137], v[30:33], v[94:97], v[134:137]
	v_mfma_f32_16x16x32_bf16 v[134:137], v[34:37], v[98:101], v[134:137]
	v_mfma_f32_16x16x32_bf16 v[134:137], v[38:41], v[102:105], v[134:137]
	v_mfma_f32_16x16x32_bf16 v[134:137], v[42:45], v[106:109], v[134:137]
	v_mfma_f32_16x16x32_bf16 v[134:137], v[46:49], v[110:113], v[134:137]
	v_mfma_f32_16x16x32_bf16 v[134:137], v[50:53], v[114:117], v[134:137]
	v_mfma_f32_16x16x32_bf16 v[134:137], v[54:57], v[118:121], v[134:137]
	v_mfma_f32_16x16x32_bf16 v[134:137], v[58:61], v[122:125], v[134:137]
	v_mfma_f32_16x16x32_bf16 v[134:137], v[62:65], v[126:129], v[134:137]
	global_load_dwordx4 v[2:5], v132, s[8:9] offset:1024
	global_load_dwordx4 v[6:9], v132, s[8:9] offset:1088
	global_load_dwordx4 v[10:13], v132, s[8:9] offset:1152
	global_load_dwordx4 v[14:17], v132, s[8:9] offset:1216
	global_load_dwordx4 v[18:21], v132, s[8:9] offset:1280
	global_load_dwordx4 v[22:25], v132, s[8:9] offset:1344
	global_load_dwordx4 v[26:29], v132, s[8:9] offset:1408
	global_load_dwordx4 v[30:33], v132, s[8:9] offset:1472
	global_load_dwordx4 v[34:37], v132, s[8:9] offset:1536
	global_load_dwordx4 v[38:41], v132, s[8:9] offset:1600
	global_load_dwordx4 v[42:45], v132, s[8:9] offset:1664
	global_load_dwordx4 v[46:49], v132, s[8:9] offset:1728
	global_load_dwordx4 v[50:53], v132, s[8:9] offset:1792
	global_load_dwordx4 v[54:57], v132, s[8:9] offset:1856
	global_load_dwordx4 v[58:61], v132, s[8:9] offset:1920
	global_load_dwordx4 v[62:65], v132, s[8:9] offset:1984
	global_load_dwordx4 v[66:69], v133, s[10:11]
	global_load_dwordx4 v[70:73], v133, s[10:11] offset:64
	v_add_u32_e32 v133, 0x8000, v133
	global_load_dwordx4 v[74:77], v133, s[10:11]
	global_load_dwordx4 v[78:81], v133, s[10:11] offset:64
	v_add_u32_e32 v133, 0x8000, v133
	global_load_dwordx4 v[82:85], v133, s[10:11]
	global_load_dwordx4 v[86:89], v133, s[10:11] offset:64
	v_add_u32_e32 v133, 0x8000, v133
	global_load_dwordx4 v[90:93], v133, s[10:11]
	global_load_dwordx4 v[94:97], v133, s[10:11] offset:64
	v_add_u32_e32 v133, 0x8000, v133
	global_load_dwordx4 v[98:101], v133, s[10:11]
	global_load_dwordx4 v[102:105], v133, s[10:11] offset:64
	v_add_u32_e32 v133, 0x8000, v133
	global_load_dwordx4 v[106:109], v133, s[10:11]
	global_load_dwordx4 v[110:113], v133, s[10:11] offset:64
	v_add_u32_e32 v133, 0x8000, v133
	global_load_dwordx4 v[114:117], v133, s[10:11]
	global_load_dwordx4 v[118:121], v133, s[10:11] offset:64
	v_add_u32_e32 v133, 0x8000, v133
	global_load_dwordx4 v[122:125], v133, s[10:11]
	global_load_dwordx4 v[126:129], v133, s[10:11] offset:64
	v_add_u32_e32 v133, 0x8000, v133
	s_waitcnt vmcnt(0)
	v_mfma_f32_16x16x32_bf16 v[134:137], v[2:5], v[66:69], v[134:137]
	v_mfma_f32_16x16x32_bf16 v[134:137], v[6:9], v[70:73], v[134:137]
	v_mfma_f32_16x16x32_bf16 v[134:137], v[10:13], v[74:77], v[134:137]
	v_mfma_f32_16x16x32_bf16 v[134:137], v[14:17], v[78:81], v[134:137]
	v_mfma_f32_16x16x32_bf16 v[134:137], v[18:21], v[82:85], v[134:137]
	v_mfma_f32_16x16x32_bf16 v[134:137], v[22:25], v[86:89], v[134:137]
	v_mfma_f32_16x16x32_bf16 v[134:137], v[26:29], v[90:93], v[134:137]
	v_mfma_f32_16x16x32_bf16 v[134:137], v[30:33], v[94:97], v[134:137]
	v_mfma_f32_16x16x32_bf16 v[134:137], v[34:37], v[98:101], v[134:137]
	v_mfma_f32_16x16x32_bf16 v[134:137], v[38:41], v[102:105], v[134:137]
	v_mfma_f32_16x16x32_bf16 v[134:137], v[42:45], v[106:109], v[134:137]
	v_mfma_f32_16x16x32_bf16 v[134:137], v[46:49], v[110:113], v[134:137]
	v_mfma_f32_16x16x32_bf16 v[134:137], v[50:53], v[114:117], v[134:137]
	v_mfma_f32_16x16x32_bf16 v[134:137], v[54:57], v[118:121], v[134:137]
	v_mfma_f32_16x16x32_bf16 v[134:137], v[58:61], v[122:125], v[134:137]
	v_mfma_f32_16x16x32_bf16 v[134:137], v[62:65], v[126:129], v[134:137]
	global_load_dwordx4 v[2:5], v132, s[8:9] offset:2048
	global_load_dwordx4 v[6:9], v132, s[8:9] offset:2112
	global_load_dwordx4 v[10:13], v132, s[8:9] offset:2176
	global_load_dwordx4 v[14:17], v132, s[8:9] offset:2240
	global_load_dwordx4 v[18:21], v132, s[8:9] offset:2304
	global_load_dwordx4 v[22:25], v132, s[8:9] offset:2368
	global_load_dwordx4 v[26:29], v132, s[8:9] offset:2432
	global_load_dwordx4 v[30:33], v132, s[8:9] offset:2496
	global_load_dwordx4 v[34:37], v132, s[8:9] offset:2560
	global_load_dwordx4 v[38:41], v132, s[8:9] offset:2624
	global_load_dwordx4 v[42:45], v132, s[8:9] offset:2688
	global_load_dwordx4 v[46:49], v132, s[8:9] offset:2752
	global_load_dwordx4 v[50:53], v132, s[8:9] offset:2816
	global_load_dwordx4 v[54:57], v132, s[8:9] offset:2880
	global_load_dwordx4 v[58:61], v132, s[8:9] offset:2944
	global_load_dwordx4 v[62:65], v132, s[8:9] offset:3008
	global_load_dwordx4 v[66:69], v133, s[10:11]
	global_load_dwordx4 v[70:73], v133, s[10:11] offset:64
	v_add_u32_e32 v133, 0x8000, v133
	global_load_dwordx4 v[74:77], v133, s[10:11]
	global_load_dwordx4 v[78:81], v133, s[10:11] offset:64
	v_add_u32_e32 v133, 0x8000, v133
	global_load_dwordx4 v[82:85], v133, s[10:11]
	global_load_dwordx4 v[86:89], v133, s[10:11] offset:64
	v_add_u32_e32 v133, 0x8000, v133
	global_load_dwordx4 v[90:93], v133, s[10:11]
	global_load_dwordx4 v[94:97], v133, s[10:11] offset:64
	v_add_u32_e32 v133, 0x8000, v133
	global_load_dwordx4 v[98:101], v133, s[10:11]
	global_load_dwordx4 v[102:105], v133, s[10:11] offset:64
	v_add_u32_e32 v133, 0x8000, v133
	global_load_dwordx4 v[106:109], v133, s[10:11]
	global_load_dwordx4 v[110:113], v133, s[10:11] offset:64
	v_add_u32_e32 v133, 0x8000, v133
	global_load_dwordx4 v[114:117], v133, s[10:11]
	global_load_dwordx4 v[118:121], v133, s[10:11] offset:64
	v_add_u32_e32 v133, 0x8000, v133
	global_load_dwordx4 v[122:125], v133, s[10:11]
	global_load_dwordx4 v[126:129], v133, s[10:11] offset:64
	v_add_u32_e32 v133, 0x8000, v133
	s_waitcnt vmcnt(0)
	v_mfma_f32_16x16x32_bf16 v[134:137], v[2:5], v[66:69], v[134:137]
	v_mfma_f32_16x16x32_bf16 v[134:137], v[6:9], v[70:73], v[134:137]
	v_mfma_f32_16x16x32_bf16 v[134:137], v[10:13], v[74:77], v[134:137]
	v_mfma_f32_16x16x32_bf16 v[134:137], v[14:17], v[78:81], v[134:137]
	v_mfma_f32_16x16x32_bf16 v[134:137], v[18:21], v[82:85], v[134:137]
	v_mfma_f32_16x16x32_bf16 v[134:137], v[22:25], v[86:89], v[134:137]
	v_mfma_f32_16x16x32_bf16 v[134:137], v[26:29], v[90:93], v[134:137]
	v_mfma_f32_16x16x32_bf16 v[134:137], v[30:33], v[94:97], v[134:137]
	v_mfma_f32_16x16x32_bf16 v[134:137], v[34:37], v[98:101], v[134:137]
	v_mfma_f32_16x16x32_bf16 v[134:137], v[38:41], v[102:105], v[134:137]
	v_mfma_f32_16x16x32_bf16 v[134:137], v[42:45], v[106:109], v[134:137]
	v_mfma_f32_16x16x32_bf16 v[134:137], v[46:49], v[110:113], v[134:137]
	v_mfma_f32_16x16x32_bf16 v[134:137], v[50:53], v[114:117], v[134:137]
	v_mfma_f32_16x16x32_bf16 v[134:137], v[54:57], v[118:121], v[134:137]
	v_mfma_f32_16x16x32_bf16 v[134:137], v[58:61], v[122:125], v[134:137]
	v_mfma_f32_16x16x32_bf16 v[134:137], v[62:65], v[126:129], v[134:137]
	global_load_dwordx4 v[2:5], v132, s[8:9] offset:3072
	global_load_dwordx4 v[6:9], v132, s[8:9] offset:3136
	global_load_dwordx4 v[10:13], v132, s[8:9] offset:3200
	global_load_dwordx4 v[14:17], v132, s[8:9] offset:3264
	global_load_dwordx4 v[18:21], v132, s[8:9] offset:3328
	global_load_dwordx4 v[22:25], v132, s[8:9] offset:3392
	global_load_dwordx4 v[26:29], v132, s[8:9] offset:3456
	global_load_dwordx4 v[30:33], v132, s[8:9] offset:3520
	global_load_dwordx4 v[34:37], v132, s[8:9] offset:3584
	global_load_dwordx4 v[38:41], v132, s[8:9] offset:3648
	global_load_dwordx4 v[42:45], v132, s[8:9] offset:3712
	global_load_dwordx4 v[46:49], v132, s[8:9] offset:3776
	global_load_dwordx4 v[50:53], v132, s[8:9] offset:3840
	global_load_dwordx4 v[54:57], v132, s[8:9] offset:3904
	global_load_dwordx4 v[58:61], v132, s[8:9] offset:3968
	global_load_dwordx4 v[62:65], v132, s[8:9] offset:4032
	global_load_dwordx4 v[66:69], v133, s[10:11]
	global_load_dwordx4 v[70:73], v133, s[10:11] offset:64
	v_add_u32_e32 v133, 0x8000, v133
	global_load_dwordx4 v[74:77], v133, s[10:11]
	global_load_dwordx4 v[78:81], v133, s[10:11] offset:64
	v_add_u32_e32 v133, 0x8000, v133
	global_load_dwordx4 v[82:85], v133, s[10:11]
	global_load_dwordx4 v[86:89], v133, s[10:11] offset:64
	v_add_u32_e32 v133, 0x8000, v133
	global_load_dwordx4 v[90:93], v133, s[10:11]
	global_load_dwordx4 v[94:97], v133, s[10:11] offset:64
	v_add_u32_e32 v133, 0x8000, v133
	global_load_dwordx4 v[98:101], v133, s[10:11]
	global_load_dwordx4 v[102:105], v133, s[10:11] offset:64
	v_add_u32_e32 v133, 0x8000, v133
	global_load_dwordx4 v[106:109], v133, s[10:11]
	global_load_dwordx4 v[110:113], v133, s[10:11] offset:64
	v_add_u32_e32 v133, 0x8000, v133
	global_load_dwordx4 v[114:117], v133, s[10:11]
	global_load_dwordx4 v[118:121], v133, s[10:11] offset:64
	v_add_u32_e32 v133, 0x8000, v133
	global_load_dwordx4 v[122:125], v133, s[10:11]
	global_load_dwordx4 v[126:129], v133, s[10:11] offset:64
	v_add_u32_e32 v133, 0x8000, v133
	s_waitcnt vmcnt(0)
; template <int MODE> __device__ __forceinline__ void gemm_epilogue(f32x4 (&acc)[2][2][4][2], const GD& g, const pg8::Unit& u, int wr, int wc, int fr, int fq, LAS unsigned char* lds, const float (&rsv)[2][4]) {
;     ...
;             for (int m = 0; m < 4; ++m) { const float rs = rsqrtf(rsv[ai][m] * (1.f / DM) + EPS);
; #pragma unroll
;                 for (int bj = 0; bj < 2; ++bj)
; #pragma unroll
;                     for (int n = 0; n < 2; ++n) acc[ai][bj][m][n] = acc[ai][bj][m][n] * rs; }
;     ...
;                 for (int m = 0; m < 4; ++m) { const int row = rt + ai * 128 + m * 16;
; #pragma unroll
;                     for (int n = 0; n < 2; ++n) { f32x4 v = acc[ai][0][m][n];
; #pragma unroll
;                         for (int j = 0; j < 4; ++j) { const int hh = 8 * fq + 4 * n + j; const float x = v[j] + bfv[hh];
;                             FL[(size_t)((row >> 12) * 16 + hh) * 4096 + (row & 4095)] = fminf(x, 0.f) - __logf(1.f + __expf(-fabsf(x))); } } }
	v_mfma_f32_16x16x32_bf16 v[134:137], v[2:5], v[66:69], v[134:137]
	v_mfma_f32_16x16x32_bf16 v[134:137], v[6:9], v[70:73], v[134:137]
	v_mfma_f32_16x16x32_bf16 v[134:137], v[10:13], v[74:77], v[134:137]
	v_mfma_f32_16x16x32_bf16 v[134:137], v[14:17], v[78:81], v[134:137]
	v_mfma_f32_16x16x32_bf16 v[134:137], v[18:21], v[82:85], v[134:137]
	v_mfma_f32_16x16x32_bf16 v[134:137], v[22:25], v[86:89], v[134:137]
	v_mfma_f32_16x16x32_bf16 v[134:137], v[26:29], v[90:93], v[134:137]
	v_mfma_f32_16x16x32_bf16 v[134:137], v[30:33], v[94:97], v[134:137]
	v_mfma_f32_16x16x32_bf16 v[134:137], v[34:37], v[98:101], v[134:137]
	v_mfma_f32_16x16x32_bf16 v[134:137], v[38:41], v[102:105], v[134:137]
	v_mfma_f32_16x16x32_bf16 v[134:137], v[42:45], v[106:109], v[134:137]
	v_mfma_f32_16x16x32_bf16 v[134:137], v[46:49], v[110:113], v[134:137]
	v_mfma_f32_16x16x32_bf16 v[134:137], v[50:53], v[114:117], v[134:137]
	v_mfma_f32_16x16x32_bf16 v[134:137], v[54:57], v[118:121], v[134:137]
	v_mfma_f32_16x16x32_bf16 v[134:137], v[58:61], v[122:125], v[134:137]
	v_mfma_f32_16x16x32_bf16 v[134:137], v[62:65], v[126:129], v[134:137]
	v_lshl_add_u32 v138, v131, 2, s6
	v_lshlrev_b32_e32 v139, 2, v138
	s_add_u32 s8, s30, 0x50000
	s_addc_u32 s9, s31, 0
	global_load_dwordx4 v[140:143], v139, s[8:9]
	v_readlane_b32 s0, v254, 27
	v_readlane_b32 s1, v254, 28
	v_lshlrev_b32_e32 v144, 2, v130
	v_mov_b32_e32 v147, 0xbfb8aa3b
	s_load_dwordx2 s[0:1], s[0:1], 0x58
	s_add_u32 s2, s30, s7
	s_addc_u32 s3, s31, 0
	s_waitcnt lgkmcnt(0)
	global_load_dword v145, v144, s[0:1]
	s_nop 7
	s_waitcnt vmcnt(0)
	v_fmamk_f32 v152, v140, 0x3a000000, v203
	v_cmp_gt_f32_e32 vcc, s80, v152
	v_mul_f32_e32 v153, 0x4b800000, v152
	s_nop 0
	v_cndmask_b32_e32 v152, v152, v153, vcc
	v_rsq_f32_e32 v152, v152
	s_nop 0
	v_mul_f32_e32 v153, 0x45800000, v152
	v_cndmask_b32_e32 v152, v152, v153, vcc
	v_mul_f32_e32 v134, v134, v152
	v_add_f32_e32 v134, v134, v145
	v_mul_f32_e64 v153, |v134|, v147
	v_exp_f32_e32 v153, v153
	s_nop 0
	v_add_f32_e32 v153, 1.0, v153
	v_log_f32_e32 v153, v153
	s_nop 0
	v_mul_f32_e32 v154, 0x3f317217, v153
	v_fma_f32 v154, v153, s85, -v154
	v_fmac_f32_e32 v154, 0x3377d1cf, v153
	v_fmac_f32_e32 v154, 0x3f317217, v153
	v_min_f32_e32 v148, 0, v134
	v_sub_f32_e32 v148, v148, v154
	v_fmamk_f32 v152, v141, 0x3a000000, v203
	v_cmp_gt_f32_e32 vcc, s80, v152
	v_mul_f32_e32 v153, 0x4b800000, v152
	s_nop 0
	v_cndmask_b32_e32 v152, v152, v153, vcc
	v_rsq_f32_e32 v152, v152
	s_nop 0
	v_mul_f32_e32 v153, 0x45800000, v152
	v_cndmask_b32_e32 v152, v152, v153, vcc
	v_mul_f32_e32 v135, v135, v152
	v_add_f32_e32 v135, v135, v145
	v_mul_f32_e64 v153, |v135|, v147
	v_exp_f32_e32 v153, v153
	s_nop 0
	v_add_f32_e32 v153, 1.0, v153
	v_log_f32_e32 v153, v153
	s_nop 0
	v_mul_f32_e32 v154, 0x3f317217, v153
	v_fma_f32 v154, v153, s85, -v154
	v_fmac_f32_e32 v154, 0x3377d1cf, v153
	v_fmac_f32_e32 v154, 0x3f317217, v153
	v_min_f32_e32 v149, 0, v135
	v_sub_f32_e32 v149, v149, v154
	v_fmamk_f32 v152, v142, 0x3a000000, v203
	v_cmp_gt_f32_e32 vcc, s80, v152
	v_mul_f32_e32 v153, 0x4b800000, v152
	s_nop 0
	v_cndmask_b32_e32 v152, v152, v153, vcc
	v_rsq_f32_e32 v152, v152
	s_nop 0
	v_mul_f32_e32 v153, 0x45800000, v152
	v_cndmask_b32_e32 v152, v152, v153, vcc
	v_mul_f32_e32 v136, v136, v152
	v_add_f32_e32 v136, v136, v145
	v_mul_f32_e64 v153, |v136|, v147
	v_exp_f32_e32 v153, v153
	s_nop 0
	v_add_f32_e32 v153, 1.0, v153
	v_log_f32_e32 v153, v153
	s_nop 0
	v_mul_f32_e32 v154, 0x3f317217, v153
	v_fma_f32 v154, v153, s85, -v154
	v_fmac_f32_e32 v154, 0x3377d1cf, v153
	v_fmac_f32_e32 v154, 0x3f317217, v153
	v_min_f32_e32 v150, 0, v136
	v_sub_f32_e32 v150, v150, v154
	v_fmamk_f32 v152, v143, 0x3a000000, v203
	v_cmp_gt_f32_e32 vcc, s80, v152
	v_mul_f32_e32 v153, 0x4b800000, v152
	s_nop 0
	v_cndmask_b32_e32 v152, v152, v153, vcc
	v_rsq_f32_e32 v152, v152
	s_nop 0
	v_mul_f32_e32 v153, 0x45800000, v152
	v_cndmask_b32_e32 v152, v152, v153, vcc
	v_mul_f32_e32 v137, v137, v152
	v_add_f32_e32 v137, v137, v145
	v_mul_f32_e64 v153, |v137|, v147
	v_exp_f32_e32 v153, v153
	s_nop 0
	v_add_f32_e32 v153, 1.0, v153
	v_log_f32_e32 v153, v153
	s_nop 0
	v_mul_f32_e32 v154, 0x3f317217, v153
	v_fma_f32 v154, v153, s85, -v154
	v_fmac_f32_e32 v154, 0x3377d1cf, v153
	v_fmac_f32_e32 v154, 0x3f317217, v153
	v_min_f32_e32 v151, 0, v137
	v_sub_f32_e32 v151, v151, v154
	global_store_dwordx4 v146, v[148:151], s[2:3]
